# v33: on top of v31, the staging->matmul barrier at the RG-LRU loop top removed (made redundant by the window move; kept for the first task only)
# speedup vs baseline: 1.0036x; 1.0036x over previous
.LBB0_307:
	s_and_b32 s41, s40, 7
	s_cmp_eq_u32 s41, s2
	s_cbranch_scc1 .LBB0_309
	s_lshl_b32 s0, s41, 6
	v_or_b32_e32 v18, s0, v121
	s_mov_b64 s[42:43], s[52:53]
	v_readlane_b32 s52, v254, 60
	v_lshlrev_b32_e32 v38, 2, v18
	v_mov_b32_e32 v39, v196
	v_readlane_b32 s64, v255, 8
	v_readlane_b32 s65, v255, 9
	v_readlane_b32 s53, v254, 61
	v_readlane_b32 s54, v254, 62
	v_readlane_b32 s55, v254, 63
	v_readlane_b32 s56, v255, 0
	v_readlane_b32 s57, v255, 1
	v_readlane_b32 s58, v255, 2
	v_readlane_b32 s59, v255, 3
	v_readlane_b32 s60, v255, 4
	v_readlane_b32 s61, v255, 5
	v_readlane_b32 s62, v255, 6
	v_readlane_b32 s63, v255, 7
	v_readlane_b32 s66, v255, 10
	v_readlane_b32 s67, v255, 11
	v_lshl_add_u64 v[50:51], s[64:65], 0, v[38:39]
	s_mov_b64 s[16:17], 0x1000
	s_movk_i32 s1, 0x1000
	s_nop 1
	global_load_dwordx4 v[22:25], v38, s[66:67] offset:16
	global_load_dwordx4 v[18:21], v38, s[64:65] offset:16
	global_load_dwordx4 v[30:33], v38, s[66:67]
	global_load_dwordx4 v[26:29], v38, s[64:65]
	global_load_dwordx4 v[34:37], v38, s[64:65] offset:2064
	s_nop 0
	global_load_dwordx4 v[38:41], v38, s[64:65] offset:2048
	v_lshl_add_u64 v[42:43], v[50:51], 0, s[16:17]
	v_add_co_u32_e32 v52, vcc, s1, v50
	s_mov_b64 s[16:17], 0x1800
	v_or_b32_e32 v58, s0, v120
	v_readlane_b32 s52, v255, 12
	v_readlane_b32 s0, v255, 43
	v_addc_co_u32_e32 v53, vcc, 0, v51, vcc
	v_lshl_add_u64 v[50:51], v[50:51], 0, s[16:17]
	v_lshlrev_b32_e32 v58, 2, v58
	v_readlane_b32 s54, v255, 14
	v_readlane_b32 s55, v255, 15
	v_readlane_b32 s1, v255, 44
	global_load_dwordx4 v[46:49], v[52:53], off
	s_nop 0
	global_load_dwordx4 v[42:45], v[42:43], off offset:16
	s_nop 0
	global_load_dwordx4 v[54:57], v[52:53], off offset:2048
	s_nop 0
	global_load_dwordx4 v[50:53], v[50:51], off offset:16
	v_readlane_b32 s58, v255, 18
	v_readlane_b32 s59, v255, 19
	global_load_dword v153, v58, s[54:55]
	s_nop 3
	global_load_dword v154, v58, s[58:59]
	global_load_dword v155, v58, s[0:1]
	s_lshl_b32 s0, s41, 13
	s_mov_b32 s1, s46
	v_lshl_add_u64 v[74:75], v[96:97], 0, s[0:1]
	global_load_dwordx4 v[70:73], v[74:75], off
	global_load_dwordx4 v[66:69], v[74:75], off offset:64
	global_load_dwordx4 v[62:65], v[74:75], off offset:2048
	global_load_dwordx4 v[58:61], v[74:75], off offset:2112
	v_add_co_u32_e32 v74, vcc, 0x1000, v74
	v_readlane_b32 s60, v255, 20
	s_nop 0
	v_addc_co_u32_e32 v75, vcc, 0, v75, vcc
	global_load_dwordx4 v[86:89], v[74:75], off
	global_load_dwordx4 v[82:85], v[74:75], off offset:64
	global_load_dwordx4 v[78:81], v[74:75], off offset:2048
	s_nop 0
	global_load_dwordx4 v[74:77], v[74:75], off offset:2112
	v_readlane_b32 s61, v255, 21
	v_readlane_b32 s62, v255, 22
	v_readlane_b32 s63, v255, 23
	v_readlane_b32 s53, v255, 13
	v_readlane_b32 s62, v255, 51
	v_readlane_b32 s60, v255, 49
	s_mov_b64 s[52:53], s[42:43]
	v_readlane_b32 s63, v255, 52
	v_readlane_b32 s61, v255, 50
	s_mov_b32 s2, s41
	v_readlane_b32 s56, v255, 16
	v_readlane_b32 s57, v255, 17
	v_readlane_b32 s64, v255, 24
	v_readlane_b32 s65, v255, 25
	v_readlane_b32 s66, v255, 26
	v_readlane_b32 s67, v255, 27
	s_waitcnt vmcnt(0)
	s_barrier
	v_lshlrev_b32_e32 v98, 16, v6
	v_and_b32_e32 v99, 0xffff0000, v6
	v_pk_fma_f32 v[98:99], v[26:27], v[98:99], v[30:31]
	v_lshlrev_b32_e32 v100, 16, v2
	v_and_b32_e32 v101, 0xffff0000, v2
	v_pk_fma_f32 v[98:99], v[38:39], v[100:101], v[98:99]
	v_lshlrev_b32_e32 v100, 16, v10
	v_and_b32_e32 v101, 0xffff0000, v10
	v_pk_fma_f32 v[98:99], v[46:47], v[100:101], v[98:99]
	v_lshlrev_b32_e32 v100, 16, v14
	v_and_b32_e32 v101, 0xffff0000, v14
	v_pk_fma_f32 v[98:99], v[54:55], v[100:101], v[98:99]
	v_lshlrev_b32_e32 v100, 16, v7
	v_and_b32_e32 v101, 0xffff0000, v7
	v_pk_fma_f32 v[100:101], v[28:29], v[100:101], v[32:33]
	v_lshlrev_b32_e32 v102, 16, v3
	v_and_b32_e32 v103, 0xffff0000, v3
	v_pk_fma_f32 v[100:101], v[40:41], v[102:103], v[100:101]
	v_lshlrev_b32_e32 v102, 16, v11
	v_and_b32_e32 v103, 0xffff0000, v11
	v_pk_fma_f32 v[100:101], v[48:49], v[102:103], v[100:101]
	v_lshlrev_b32_e32 v102, 16, v15
	v_and_b32_e32 v103, 0xffff0000, v15
	v_pk_fma_f32 v[100:101], v[56:57], v[102:103], v[100:101]
	v_lshlrev_b32_e32 v102, 16, v8
	v_and_b32_e32 v103, 0xffff0000, v8
	v_pk_fma_f32 v[102:103], v[18:19], v[102:103], v[22:23]
	v_lshlrev_b32_e32 v104, 16, v4
	v_and_b32_e32 v105, 0xffff0000, v4
	v_pk_fma_f32 v[102:103], v[34:35], v[104:105], v[102:103]
	v_lshlrev_b32_e32 v104, 16, v12
	v_and_b32_e32 v105, 0xffff0000, v12
	v_pk_fma_f32 v[102:103], v[42:43], v[104:105], v[102:103]
	v_lshlrev_b32_e32 v104, 16, v16
	v_and_b32_e32 v105, 0xffff0000, v16
	v_pk_fma_f32 v[102:103], v[50:51], v[104:105], v[102:103]
	v_lshlrev_b32_e32 v104, 16, v9
	v_and_b32_e32 v105, 0xffff0000, v9
	v_pk_fma_f32 v[104:105], v[20:21], v[104:105], v[24:25]
	v_lshlrev_b32_e32 v106, 16, v5
	v_and_b32_e32 v107, 0xffff0000, v5
	v_pk_fma_f32 v[104:105], v[36:37], v[106:107], v[104:105]
	v_lshlrev_b32_e32 v106, 16, v13
	v_and_b32_e32 v107, 0xffff0000, v13
	v_pk_fma_f32 v[104:105], v[44:45], v[106:107], v[104:105]
	v_lshlrev_b32_e32 v106, 16, v17
	v_and_b32_e32 v107, 0xffff0000, v17
	v_pk_fma_f32 v[104:105], v[52:53], v[106:107], v[104:105]
	v_cvt_pk_bf16_f32 v106, v98, v99
	v_cvt_pk_bf16_f32 v107, v100, v101
	v_cvt_pk_bf16_f32 v108, v102, v103
	v_add_u32_e32 v110, v122, v90
	v_cvt_pk_bf16_f32 v109, v104, v105
	ds_write_b128 v110, v[106:109]
	ds_write_b128 v123, v[98:101] offset:9216
	ds_write_b128 v123, v[102:105] offset:9232
	s_waitcnt lgkmcnt(0)
	s_barrier
.LBB0_309:
	s_load_dword s15, s[78:79], 0x0
	s_waitcnt lgkmcnt(0)
	s_add_i32 s15, s15, s40
	s_cmpk_gt_i32 s15, 0x7ff
	s_cselect_b64 s[16:17], -1, 0
	s_and_b64 vcc, exec, s[16:17]
	s_cbranch_vccnz .LBB0_319
	s_lshl_b32 s0, s15, 8
	s_and_b32 s42, s15, 0xffffffc0
	s_and_b32 s33, s0, 0x3800
	s_lshl_b32 s0, s15, 7
	v_add_u32_e32 v14, s42, v124
	s_and_b32 s0, s0, 0x380
	s_mov_b32 s1, s46
	v_mov_b32_e32 v2, v196
	v_mov_b32_e32 v3, v196
	v_lshl_add_u64 v[98:99], v[92:93], 0, s[0:1]
	v_cmp_lt_i32_e32 vcc, -1, v14
	v_mov_b64_e32 v[6:7], v[2:3]
	v_mov_b64_e32 v[8:9], v[2:3]
	s_and_saveexec_b64 s[0:1], vcc
	s_cbranch_execz .LBB0_312
	v_add_u32_e32 v4, s33, v14
	s_movk_i32 s43, 0xc00
	v_mad_u64_u32 v[4:5], s[44:45], v4, s43, v[98:99]
	global_load_dwordx4 v[6:9], v[4:5], off

.LBB0_327:
	s_or_b64 exec, exec, s[0:1]
	s_waitcnt lgkmcnt(0)
	ds_read_b128 v[114:117], v147
	ds_read_b128 v[164:167], v147 offset:64
	s_waitcnt lgkmcnt(1)
	v_mfma_f32_16x16x32_bf16 v[168:171], v[114:117], v[70:73], 0
	v_add_u32_e32 v113, 0x6400, v148
	v_mov_b32_e32 v178, 1.0
	v_mfma_f32_16x16x32_bf16 v[172:175], v[114:117], v[62:65], 0
	s_waitcnt lgkmcnt(0)
	v_mfma_f32_16x16x32_bf16 v[168:171], v[164:167], v[66:69], v[168:171]
	v_mfma_f32_16x16x32_bf16 v[172:175], v[164:167], v[58:61], v[172:175]
	s_nop 7
	ds_write2_b32 v113, v168, v172 offset1:16
	ds_write2_b32 v113, v169, v173 offset0:64 offset1:80
	ds_write2_b32 v113, v170, v174 offset0:128 offset1:144
	ds_write2_b32 v113, v171, v175 offset0:192 offset1:208
	v_mfma_f32_16x16x32_bf16 v[168:171], v[114:117], v[86:89], 0
	v_mfma_f32_16x16x32_bf16 v[114:117], v[114:117], v[78:81], 0
	v_mfma_f32_16x16x32_bf16 v[168:171], v[164:167], v[82:85], v[168:171]
	v_mfma_f32_16x16x32_bf16 v[114:117], v[164:167], v[74:77], v[114:117]
	s_nop 7
	ds_write2_b32 v113, v168, v114 offset0:32 offset1:48
	ds_write2_b32 v113, v169, v115 offset0:96 offset1:112
	ds_write2_b32 v113, v170, v116 offset0:160 offset1:176
	ds_write2_b32 v113, v171, v117 offset0:224 offset1:240
	s_waitcnt lgkmcnt(0)
	s_barrier
	ds_read2st64_b32 v[198:199], v129 offset0:36 offset1:100
	ds_read2st64_b32 v[200:201], v131 offset0:36 offset1:100
	ds_read2st64_b32 v[202:203], v133 offset0:36 offset1:100
	ds_read2st64_b32 v[204:205], v135 offset0:36 offset1:100
	ds_read2st64_b32 v[206:207], v137 offset0:36 offset1:100
	ds_read2st64_b32 v[208:209], v139 offset0:36 offset1:100
	ds_read2st64_b32 v[210:211], v141 offset0:36 offset1:100
	ds_read2st64_b32 v[212:213], v143 offset0:36 offset1:100
	ds_read_b32 v214, v130 offset:41984
	ds_read_b32 v215, v132 offset:41984
	ds_read_b32 v216, v134 offset:41984
	ds_read_b32 v217, v136 offset:41984
	ds_read_b32 v218, v138 offset:41984
	ds_read_b32 v219, v140 offset:41984
	ds_read_b32 v220, v142 offset:41984
	ds_read_b32 v221, v144 offset:41984
	s_waitcnt lgkmcnt(8)
	v_add_f32_e32 v199, v153, v199
	v_add_f32_e32 v201, v153, v201
	v_add_f32_e32 v203, v153, v203
	v_add_f32_e32 v205, v153, v205
	v_add_f32_e32 v207, v153, v207
	v_add_f32_e32 v209, v153, v209
	v_add_f32_e32 v211, v153, v211
	v_add_f32_e32 v213, v153, v213
	v_mul_f32_e32 v199, 0xbfb8aa3b, v199
	v_mul_f32_e32 v201, 0xbfb8aa3b, v201
	v_mul_f32_e32 v203, 0xbfb8aa3b, v203
	v_mul_f32_e32 v205, 0xbfb8aa3b, v205
	v_mul_f32_e32 v207, 0xbfb8aa3b, v207
	v_mul_f32_e32 v209, 0xbfb8aa3b, v209
	v_mul_f32_e32 v211, 0xbfb8aa3b, v211
	v_mul_f32_e32 v213, 0xbfb8aa3b, v213
	v_exp_f32_e32 v199, v199
	v_exp_f32_e32 v201, v201
	v_exp_f32_e32 v203, v203
	v_exp_f32_e32 v205, v205
	v_exp_f32_e32 v207, v207
	v_exp_f32_e32 v209, v209
	v_exp_f32_e32 v211, v211
	v_exp_f32_e32 v213, v213
	s_waitcnt lgkmcnt(0)
	v_add_f32_e32 v214, v154, v214
	v_add_f32_e32 v215, v154, v215
	v_add_f32_e32 v216, v154, v216
	v_add_f32_e32 v217, v154, v217
	v_add_f32_e32 v218, v154, v218
	v_add_f32_e32 v219, v154, v219
	v_add_f32_e32 v220, v154, v220
	v_add_f32_e32 v221, v154, v221
	v_add_f32_e32 v199, 1.0, v199
	v_add_f32_e32 v201, 1.0, v201
	v_add_f32_e32 v203, 1.0, v203
	v_add_f32_e32 v205, 1.0, v205
	v_add_f32_e32 v207, 1.0, v207
	v_add_f32_e32 v209, 1.0, v209
	v_add_f32_e32 v211, 1.0, v211
	v_add_f32_e32 v213, 1.0, v213
	v_rcp_f32_e32 v199, v199
	v_rcp_f32_e32 v201, v201
	v_rcp_f32_e32 v203, v203
	v_rcp_f32_e32 v205, v205
	v_rcp_f32_e32 v207, v207
	v_rcp_f32_e32 v209, v209
	v_rcp_f32_e32 v211, v211
	v_rcp_f32_e32 v213, v213
	v_mul_f32_e32 v214, 0xbfb8aa3b, v214
	v_mul_f32_e32 v215, 0xbfb8aa3b, v215
	v_mul_f32_e32 v216, 0xbfb8aa3b, v216
	v_mul_f32_e32 v217, 0xbfb8aa3b, v217
	v_mul_f32_e32 v218, 0xbfb8aa3b, v218
	v_mul_f32_e32 v219, 0xbfb8aa3b, v219
	v_mul_f32_e32 v220, 0xbfb8aa3b, v220
	v_mul_f32_e32 v221, 0xbfb8aa3b, v221
	v_exp_f32_e32 v214, v214
	v_exp_f32_e32 v215, v215
	v_exp_f32_e32 v216, v216
	v_exp_f32_e32 v217, v217
	v_exp_f32_e32 v218, v218
	v_exp_f32_e32 v219, v219
	v_exp_f32_e32 v220, v220
	v_exp_f32_e32 v221, v221
	v_mul_f32_e32 v199, 0x41000000, v199
	v_mul_f32_e32 v201, 0x41000000, v201
	v_mul_f32_e32 v203, 0x41000000, v203
	v_mul_f32_e32 v205, 0x41000000, v205
	v_mul_f32_e32 v207, 0x41000000, v207
	v_mul_f32_e32 v209, 0x41000000, v209
	v_mul_f32_e32 v211, 0x41000000, v211
	v_mul_f32_e32 v213, 0x41000000, v213
	v_mul_f32_e32 v199, v155, v199
	v_mul_f32_e32 v201, v155, v201
	v_mul_f32_e32 v203, v155, v203
	v_mul_f32_e32 v205, v155, v205
	v_mul_f32_e32 v207, v155, v207
	v_mul_f32_e32 v209, v155, v209
	v_mul_f32_e32 v211, v155, v211
	v_mul_f32_e32 v213, v155, v213
	v_mul_f32_e32 v199, 0x3fb8aa3b, v199
	v_mul_f32_e32 v201, 0x3fb8aa3b, v201
	v_mul_f32_e32 v203, 0x3fb8aa3b, v203
	v_mul_f32_e32 v205, 0x3fb8aa3b, v205
	v_mul_f32_e32 v207, 0x3fb8aa3b, v207
	v_mul_f32_e32 v209, 0x3fb8aa3b, v209
	v_mul_f32_e32 v211, 0x3fb8aa3b, v211
	v_mul_f32_e32 v213, 0x3fb8aa3b, v213
	v_exp_f32_e32 v163, v199
	v_exp_f32_e32 v201, v201
	v_exp_f32_e32 v203, v203
	v_exp_f32_e32 v205, v205
	v_exp_f32_e32 v207, v207
	v_exp_f32_e32 v209, v209
	v_exp_f32_e32 v211, v211
	v_exp_f32_e32 v213, v213
	v_add_f32_e32 v214, 1.0, v214
	v_add_f32_e32 v215, 1.0, v215
	v_add_f32_e32 v216, 1.0, v216
	v_add_f32_e32 v217, 1.0, v217
	v_add_f32_e32 v218, 1.0, v218
	v_add_f32_e32 v219, 1.0, v219
	v_add_f32_e32 v220, 1.0, v220
	v_add_f32_e32 v221, 1.0, v221
	v_rcp_f32_e32 v214, v214
	v_rcp_f32_e32 v215, v215
	v_rcp_f32_e32 v216, v216
	v_rcp_f32_e32 v217, v217
	v_rcp_f32_e32 v218, v218
	v_rcp_f32_e32 v219, v219
	v_rcp_f32_e32 v220, v220
	v_rcp_f32_e32 v221, v221
	v_fma_f32 v180, -v163, v163, 1.0
	v_fma_f32 v181, -v201, v201, 1.0
	v_fma_f32 v182, -v203, v203, 1.0
	v_fma_f32 v183, -v205, v205, 1.0
	v_fma_f32 v184, -v207, v207, 1.0
	v_fma_f32 v185, -v209, v209, 1.0
	v_fma_f32 v186, -v211, v211, 1.0
	v_fma_f32 v187, -v213, v213, 1.0
	v_max_f32_e32 v180, 0, v180
	v_max_f32_e32 v181, 0, v181
	v_max_f32_e32 v182, 0, v182
	v_max_f32_e32 v183, 0, v183
	v_max_f32_e32 v184, 0, v184
	v_max_f32_e32 v185, 0, v185
	v_max_f32_e32 v186, 0, v186
	v_max_f32_e32 v187, 0, v187
	v_sqrt_f32_e32 v180, v180
	v_sqrt_f32_e32 v181, v181
	v_sqrt_f32_e32 v182, v182
	v_sqrt_f32_e32 v183, v183
	v_sqrt_f32_e32 v184, v184
	v_sqrt_f32_e32 v185, v185
	v_sqrt_f32_e32 v186, v186
	v_sqrt_f32_e32 v187, v187
	v_mul_f32_e32 v198, v198, v214
	v_mul_f32_e32 v200, v200, v215
	v_mul_f32_e32 v202, v202, v216
	v_mul_f32_e32 v204, v204, v217
	v_mul_f32_e32 v206, v206, v218
	v_mul_f32_e32 v208, v208, v219
	v_mul_f32_e32 v210, v210, v220
	v_mul_f32_e32 v212, v212, v221
	v_mul_f32_e32 v116, 0, v163
	v_fma_f32 v164, v198, v180, v116
	v_mul_f32_e32 v165, v200, v181
	v_mul_f32_e32 v166, v163, v201
	v_fmac_f32_e32 v165, v201, v164
	v_mul_f32_e32 v167, v202, v182
	v_mul_f32_e32 v169, v166, v203
	v_fmac_f32_e32 v167, v203, v165
	v_mul_f32_e32 v168, v204, v183
	v_mul_f32_e32 v171, v169, v205
	v_fmac_f32_e32 v168, v205, v167
	v_mul_f32_e32 v170, v206, v184
	v_mul_f32_e32 v173, v171, v207
	v_fmac_f32_e32 v170, v207, v168
	v_mul_f32_e32 v172, v208, v185
	v_mul_f32_e32 v175, v173, v209
	v_fmac_f32_e32 v172, v209, v170
	v_mul_f32_e32 v174, v210, v186
	v_mul_f32_e32 v176, v175, v211
	v_fmac_f32_e32 v174, v211, v172
	v_mul_f32_e32 v115, v212, v187
	v_mul_f32_e32 v114, v176, v213
	v_fmac_f32_e32 v115, v213, v174
	v_mov_b32_e32 v117, 0
	ds_write_b64 v149, v[114:115] offset:58368
	s_waitcnt lgkmcnt(0)
	s_barrier
	v_readfirstlane_b32 s68, v119
	ds_read_b64 v[226:227], v145
	ds_read_b64 v[228:229], v145 offset:512
	ds_read_b64 v[230:231], v145 offset:1024
	ds_read_b64 v[232:233], v145 offset:1536
	ds_read_b64 v[234:235], v145 offset:2048
	ds_read_b64 v[236:237], v145 offset:2560
	ds_read_b64 v[238:239], v145 offset:3072
	s_waitcnt lgkmcnt(0)
	s_cmp_lt_i32 s68, 1
	s_cbranch_scc1 .Lrnn_pfx_done
	v_mul_f32_e32 v178, v178, v226
	v_fma_f32 v117, v117, v226, v227
	s_cmp_lt_i32 s68, 2
	s_cbranch_scc1 .Lrnn_pfx_done
	v_mul_f32_e32 v178, v178, v228
	v_fma_f32 v117, v117, v228, v229
	s_cmp_lt_i32 s68, 3
	s_cbranch_scc1 .Lrnn_pfx_done
	v_mul_f32_e32 v178, v178, v230
	v_fma_f32 v117, v117, v230, v231
	s_cmp_lt_i32 s68, 4
	s_cbranch_scc1 .Lrnn_pfx_done
	v_mul_f32_e32 v178, v178, v232
	v_fma_f32 v117, v117, v232, v233
	s_cmp_lt_i32 s68, 5
	s_cbranch_scc1 .Lrnn_pfx_done
	v_mul_f32_e32 v178, v178, v234
	v_fma_f32 v117, v117, v234, v235
	s_cmp_lt_i32 s68, 6
	s_cbranch_scc1 .Lrnn_pfx_done
	v_mul_f32_e32 v178, v178, v236
	v_fma_f32 v117, v117, v236, v237
	s_cmp_lt_i32 s68, 7
	s_cbranch_scc1 .Lrnn_pfx_done
	v_mul_f32_e32 v178, v178, v238
	v_fma_f32 v117, v117, v238, v239
